# v69 with the three GEMM mainloop heads on 64-byte boundaries (fill after the peeled iteration's exit branch, never executed)
# baseline (speedup 1.0000x reference)
; #define PG8_STAGE(bufoff, gbase, voff) do { _Pragma("unroll") for (int _i = 0; _i < 2; ++_i) \
;         __builtin_amdgcn_global_load_lds((const unsigned*)((const char*)(gbase) + (voff)[_i]), (LAS unsigned*)(lds + (bufoff) + ldsw + _i * 8192), 16, 0, 0); } while (0)
; #define PG8_LDA(dst, b, h) do { _Pragma("unroll") for (int m = 0; m < 4; ++m) _Pragma("unroll") for (int k = 0; k < 2; ++k) dst[m][k] = *(const LAS bf16x8*)(lds + PG8_SA(b, h) + aoff + m * 2048 + k * 1024); } while (0)
; #define PG8_LDB(dst, b, h) do { _Pragma("unroll") for (int n = 0; n < 2; ++n) _Pragma("unroll") for (int k = 0; k < 2; ++k) dst[n][k] = *(const LAS bf16x8*)(lds + PG8_SB(b, h) + boff + n * 2048 + k * 1024); } while (0)
; #define PG8_MMA(ai, bj, At, Bt) do { __builtin_amdgcn_s_setprio(1); _Pragma("unroll") for (int m = 0; m < 4; ++m) _Pragma("unroll") for (int n = 0; n < 2; ++n) _Pragma("unroll") for (int k = 0; k < 2; ++k) \
;         acc[ai][bj][m][n] = __builtin_amdgcn_mfma_f32_16x16x32_bf16(Bt[n][k], At[m][k], acc[ai][bj][m][n], 0, 0, 0); __builtin_amdgcn_s_setprio(0); } while (0)
; #define PG8_WAIT_V(n) asm volatile("s_waitcnt vmcnt(" #n ")" ::: "memory")
; #define PG8_WAIT_L(n) asm volatile("s_waitcnt lgkmcnt(" #n ")" ::: "memory")
; #define PG8_BAR __builtin_amdgcn_s_barrier()
; #define PG8_SCHED __builtin_amdgcn_sched_barrier(0)
; __device__ __forceinline__ void gemm_phase(LAS unsigned char* lds, const Gemm g, const StaticOrder& S, const LAS Epi* Ep, const int tid) {
;     ...
;         for (int t = 0; t < nt; t += 2) {
;             const bool last = (t == nt - 2);
;             const char* a1 = cA + (size_t)(t + 1) * kstep;
;             const char* a2 = last ? nA : cA + (size_t)(t + 2) * kstep; const char* b2 = last ? nB : cB + (size_t)(t + 2) * kstep;
;             const char* a3 = a2 + kstep; const char* b3 = b2 + kstep;
;             PG8_LDB(B0, 0, 0); PG8_LDB(B1, 0, 1); PG8_SCHED; PG8_LDA(At, 0, 0); PG8_STAGE(PG8_SA(1, 1), a1 + hstepA, voffA);
;             PG8_WAIT_V(8); PG8_WAIT_L(0); PG8_BAR; PG8_MMA(0, 0, At, B0); PG8_MMA(0, 1, At, B1); PG8_BAR; PG8_SCHED;
;             PG8_LDA(At, 0, 1); PG8_STAGE(PG8_SB(0, 0), b2, voffB); PG8_STAGE(PG8_SB(0, 1), b2 + hstepB, voffB); PG8_STAGE(PG8_SA(0, 0), a2, voffA);
;             PG8_WAIT_V(8); PG8_WAIT_L(0); PG8_BAR; PG8_MMA(1, 0, At, B0); PG8_MMA(1, 1, At, B1); PG8_BAR; PG8_SCHED;
.Lstag1_skip:
	s_add_i32 s17, s14, 2
	s_add_u32 s18, s0, 0x80
	s_addc_u32 s15, s1, 0
	s_add_i32 s20, 0, 0x10000
	s_cmp_eq_u32 s66, s14
	s_cselect_b32 s15, s11, s15
	s_cselect_b32 s14, s10, s18
	v_add_u32_e32 v2, s20, v233
	s_cselect_b32 s19, s13, s16
	s_cselect_b32 s18, s12, s3
	s_add_i32 s21, 0, 0x14000
	s_waitcnt lgkmcnt(0)
	ds_read_b128 v[132:135], v2
	ds_read_b128 v[136:139], v2 offset:1024
	ds_read_b128 v[140:143], v2 offset:2048
	ds_read_b128 v[144:147], v2 offset:3072
	v_add_u32_e32 v2, s21, v233
	ds_read_b128 v[148:151], v2
	ds_read_b128 v[152:155], v2 offset:1024
	ds_read_b128 v[156:159], v2 offset:2048
	ds_read_b128 v[160:163], v2 offset:3072
	v_lshl_add_u64 v[210:211], s[0:1], 0, v[206:207]
	s_add_i32 m0, s78, 0xc000
	ds_read_b128 v[164:167], v235
	ds_read_b128 v[168:171], v235 offset:1024
	ds_read_b128 v[172:175], v235 offset:2048
	ds_read_b128 v[176:179], v235 offset:3072
	ds_read_b128 v[180:183], v235 offset:4096
	ds_read_b128 v[184:187], v235 offset:5120
	ds_read_b128 v[188:191], v235 offset:6144
	ds_read_b128 v[192:195], v235 offset:7168
	global_load_lds_dwordx4 v[210:211], off
	v_lshl_add_u64 v[210:211], s[0:1], 0, v[208:209]
	s_add_i32 m0, s78, 0xe000
	s_nop 0
	global_load_lds_dwordx4 v[210:211], off
	s_waitcnt vmcnt(8)
	s_waitcnt lgkmcnt(0)
	s_barrier
	s_setprio 1
	s_waitcnt lgkmcnt(0)
	v_mfma_f32_16x16x32_bf16 v[128:131], v[132:135], v[164:167], 0
	v_mfma_f32_16x16x32_bf16 v[120:123], v[140:143], v[164:167], 0
	v_mfma_f32_16x16x32_bf16 v[112:115], v[132:135], v[172:175], 0
	v_mfma_f32_16x16x32_bf16 v[104:107], v[140:143], v[172:175], 0
	v_mfma_f32_16x16x32_bf16 v[96:99], v[132:135], v[180:183], 0
	v_mfma_f32_16x16x32_bf16 v[88:91], v[140:143], v[180:183], 0
	v_mfma_f32_16x16x32_bf16 v[80:83], v[132:135], v[188:191], 0
	v_mfma_f32_16x16x32_bf16 v[72:75], v[140:143], v[188:191], 0
	v_mfma_f32_16x16x32_bf16 v[128:131], v[136:139], v[168:171], v[128:131]
	v_mfma_f32_16x16x32_bf16 v[120:123], v[144:147], v[168:171], v[120:123]
	v_mfma_f32_16x16x32_bf16 v[112:115], v[136:139], v[176:179], v[112:115]
	v_mfma_f32_16x16x32_bf16 v[104:107], v[144:147], v[176:179], v[104:107]
	v_mfma_f32_16x16x32_bf16 v[96:99], v[136:139], v[184:187], v[96:99]
	v_mfma_f32_16x16x32_bf16 v[88:91], v[144:147], v[184:187], v[88:91]
	v_mfma_f32_16x16x32_bf16 v[80:83], v[136:139], v[192:195], v[80:83]
	v_mfma_f32_16x16x32_bf16 v[72:75], v[144:147], v[192:195], v[72:75]
	s_setprio 0
	s_setprio 1
	v_mfma_f32_16x16x32_bf16 v[124:127], v[148:151], v[164:167], 0
	v_mfma_f32_16x16x32_bf16 v[116:119], v[156:159], v[164:167], 0
	v_mfma_f32_16x16x32_bf16 v[108:111], v[148:151], v[172:175], 0
	v_mfma_f32_16x16x32_bf16 v[100:103], v[156:159], v[172:175], 0
	v_mfma_f32_16x16x32_bf16 v[92:95], v[148:151], v[180:183], 0
	v_mfma_f32_16x16x32_bf16 v[84:87], v[156:159], v[180:183], 0
	v_mfma_f32_16x16x32_bf16 v[76:79], v[148:151], v[188:191], 0
	v_mfma_f32_16x16x32_bf16 v[68:71], v[156:159], v[188:191], 0
	v_mfma_f32_16x16x32_bf16 v[124:127], v[152:155], v[168:171], v[124:127]
	v_mfma_f32_16x16x32_bf16 v[116:119], v[160:163], v[168:171], v[116:119]
	v_mfma_f32_16x16x32_bf16 v[108:111], v[152:155], v[176:179], v[108:111]
	v_mfma_f32_16x16x32_bf16 v[100:103], v[160:163], v[176:179], v[100:103]
	v_mfma_f32_16x16x32_bf16 v[92:95], v[152:155], v[184:187], v[92:95]
	v_mfma_f32_16x16x32_bf16 v[84:87], v[160:163], v[184:187], v[84:87]
	v_mfma_f32_16x16x32_bf16 v[76:79], v[152:155], v[192:195], v[76:79]
	v_mfma_f32_16x16x32_bf16 v[68:71], v[160:163], v[192:195], v[68:71]
	s_setprio 0
	s_barrier
	s_add_i32 s20, s20, s85
	v_lshl_add_u64 v[210:211], s[18:19], 0, v[196:197]
	s_mov_b32 m0, s20
	ds_read_b128 v[164:167], v235 offset:16384
	ds_read_b128 v[168:171], v235 offset:17408
	ds_read_b128 v[172:175], v235 offset:18432
	ds_read_b128 v[176:179], v235 offset:19456
	ds_read_b128 v[180:183], v235 offset:20480
	ds_read_b128 v[184:187], v235 offset:21504
	ds_read_b128 v[188:191], v235 offset:22528
	ds_read_b128 v[192:195], v235 offset:23552
	global_load_lds_dwordx4 v[210:211], off
	s_add_i32 m0, s20, 0x2000
	v_lshl_add_u64 v[212:213], s[18:19], 0, v[200:201]
	s_add_u32 s18, s18, s39
	s_addc_u32 s19, s19, 0
	s_add_i32 s20, s21, s85
	global_load_lds_dwordx4 v[212:213], off
	v_lshl_add_u64 v[214:215], s[18:19], 0, v[196:197]
	s_mov_b32 m0, s20
	v_lshl_add_u64 v[216:217], s[18:19], 0, v[200:201]
	global_load_lds_dwordx4 v[214:215], off
	s_add_i32 m0, s20, 0x2000
	v_lshl_add_u64 v[218:219], s[14:15], 0, v[0:1]
	global_load_lds_dwordx4 v[216:217], off
	s_mov_b32 m0, s78
	v_lshl_add_u64 v[220:221], s[14:15], 0, v[198:199]
	global_load_lds_dwordx4 v[218:219], off
	s_mov_b32 m0, s56
	s_nop 0
	global_load_lds_dwordx4 v[220:221], off
	s_waitcnt vmcnt(8)
	s_waitcnt lgkmcnt(0)
	s_barrier
; #define PG8_STAGE(bufoff, gbase, voff) do { _Pragma("unroll") for (int _i = 0; _i < 2; ++_i) \
;         __builtin_amdgcn_global_load_lds((const unsigned*)((const char*)(gbase) + (voff)[_i]), (LAS unsigned*)(lds + (bufoff) + ldsw + _i * 8192), 16, 0, 0); } while (0)
; #define PG8_LDA(dst, b, h) do { _Pragma("unroll") for (int m = 0; m < 4; ++m) _Pragma("unroll") for (int k = 0; k < 2; ++k) dst[m][k] = *(const LAS bf16x8*)(lds + PG8_SA(b, h) + aoff + m * 2048 + k * 1024); } while (0)
; #define PG8_LDB(dst, b, h) do { _Pragma("unroll") for (int n = 0; n < 2; ++n) _Pragma("unroll") for (int k = 0; k < 2; ++k) dst[n][k] = *(const LAS bf16x8*)(lds + PG8_SB(b, h) + boff + n * 2048 + k * 1024); } while (0)
; #define PG8_MMA(ai, bj, At, Bt) do { __builtin_amdgcn_s_setprio(1); _Pragma("unroll") for (int m = 0; m < 4; ++m) _Pragma("unroll") for (int n = 0; n < 2; ++n) _Pragma("unroll") for (int k = 0; k < 2; ++k) \
;         acc[ai][bj][m][n] = __builtin_amdgcn_mfma_f32_16x16x32_bf16(Bt[n][k], At[m][k], acc[ai][bj][m][n], 0, 0, 0); __builtin_amdgcn_s_setprio(0); } while (0)
; #define PG8_WAIT_V(n) asm volatile("s_waitcnt vmcnt(" #n ")" ::: "memory")
; #define PG8_WAIT_L(n) asm volatile("s_waitcnt lgkmcnt(" #n ")" ::: "memory")
; #define PG8_BAR __builtin_amdgcn_s_barrier()
; #define PG8_SCHED __builtin_amdgcn_sched_barrier(0)
; __device__ __forceinline__ void gemm_phase(LAS unsigned char* lds, const Gemm g, const StaticOrder& S, const LAS Epi* Ep, const int tid) {
;     ...
;             PG8_WAIT_V(8); PG8_WAIT_L(0); PG8_BAR; PG8_MMA(1, 0, At, B0); PG8_MMA(1, 1, At, B1); PG8_BAR; PG8_SCHED;
;             PG8_LDB(B0, 1, 0); PG8_LDB(B1, 1, 1); PG8_SCHED; PG8_LDA(At, 1, 0); PG8_STAGE(PG8_SA(0, 1), a2 + hstepA, voffA);
;             PG8_WAIT_V(8); PG8_WAIT_L(0); PG8_BAR; PG8_MMA(0, 0, At, B0); PG8_MMA(0, 1, At, B1); PG8_BAR; PG8_SCHED;
	s_setprio 1
	s_waitcnt lgkmcnt(0)
	v_mfma_f32_16x16x32_bf16 v[64:67], v[132:135], v[164:167], 0
	v_mfma_f32_16x16x32_bf16 v[56:59], v[140:143], v[164:167], 0
	v_mfma_f32_16x16x32_bf16 v[48:51], v[132:135], v[172:175], 0
	v_mfma_f32_16x16x32_bf16 v[40:43], v[140:143], v[172:175], 0
	v_mfma_f32_16x16x32_bf16 v[32:35], v[132:135], v[180:183], 0
	v_mfma_f32_16x16x32_bf16 v[24:27], v[140:143], v[180:183], 0
	v_mfma_f32_16x16x32_bf16 v[16:19], v[132:135], v[188:191], 0
	v_mfma_f32_16x16x32_bf16 v[8:11], v[140:143], v[188:191], 0
	v_mfma_f32_16x16x32_bf16 v[64:67], v[136:139], v[168:171], v[64:67]
	v_mfma_f32_16x16x32_bf16 v[56:59], v[144:147], v[168:171], v[56:59]
	v_mfma_f32_16x16x32_bf16 v[48:51], v[136:139], v[176:179], v[48:51]
	v_mfma_f32_16x16x32_bf16 v[40:43], v[144:147], v[176:179], v[40:43]
	v_mfma_f32_16x16x32_bf16 v[32:35], v[136:139], v[184:187], v[32:35]
	v_mfma_f32_16x16x32_bf16 v[24:27], v[144:147], v[184:187], v[24:27]
	v_mfma_f32_16x16x32_bf16 v[16:19], v[136:139], v[192:195], v[16:19]
	v_mfma_f32_16x16x32_bf16 v[8:11], v[144:147], v[192:195], v[8:11]
	s_setprio 0
	s_setprio 1
	v_mfma_f32_16x16x32_bf16 v[60:63], v[148:151], v[164:167], 0
	v_mfma_f32_16x16x32_bf16 v[52:55], v[156:159], v[164:167], 0
	v_mfma_f32_16x16x32_bf16 v[44:47], v[148:151], v[172:175], 0
	v_mfma_f32_16x16x32_bf16 v[36:39], v[156:159], v[172:175], 0
	v_mfma_f32_16x16x32_bf16 v[28:31], v[148:151], v[180:183], 0
	v_mfma_f32_16x16x32_bf16 v[20:23], v[156:159], v[180:183], 0
	v_mfma_f32_16x16x32_bf16 v[12:15], v[148:151], v[188:191], 0
	v_mfma_f32_16x16x32_bf16 v[4:7], v[156:159], v[188:191], 0
	v_mfma_f32_16x16x32_bf16 v[60:63], v[152:155], v[168:171], v[60:63]
	v_mfma_f32_16x16x32_bf16 v[52:55], v[160:163], v[168:171], v[52:55]
	v_mfma_f32_16x16x32_bf16 v[44:47], v[152:155], v[176:179], v[44:47]
	v_mfma_f32_16x16x32_bf16 v[36:39], v[160:163], v[176:179], v[36:39]
	v_mfma_f32_16x16x32_bf16 v[28:31], v[152:155], v[184:187], v[28:31]
	v_mfma_f32_16x16x32_bf16 v[20:23], v[160:163], v[184:187], v[20:23]
	v_mfma_f32_16x16x32_bf16 v[12:15], v[152:155], v[192:195], v[12:15]
	v_mfma_f32_16x16x32_bf16 v[4:7], v[160:163], v[192:195], v[4:7]
	s_setprio 0
	s_barrier
	s_add_i32 s18, 0, 0x18000
	v_add_u32_e32 v2, s18, v233
	s_add_i32 s19, 0, 0x1c000
	ds_read_b128 v[132:135], v2
	ds_read_b128 v[136:139], v2 offset:1024
	ds_read_b128 v[140:143], v2 offset:2048
	ds_read_b128 v[144:147], v2 offset:3072
	v_add_u32_e32 v2, s19, v233
	ds_read_b128 v[148:151], v2
	ds_read_b128 v[152:155], v2 offset:1024
	ds_read_b128 v[156:159], v2 offset:2048
	ds_read_b128 v[160:163], v2 offset:3072
	s_add_u32 s14, s14, s86
	s_addc_u32 s15, s15, 0
	s_mov_b32 m0, s57
	v_lshl_add_u64 v[222:223], s[14:15], 0, v[0:1]
	ds_read_b128 v[164:167], v235 offset:32768
	ds_read_b128 v[168:171], v235 offset:33792
	ds_read_b128 v[172:175], v235 offset:34816
	ds_read_b128 v[176:179], v235 offset:35840
	ds_read_b128 v[180:183], v235 offset:36864
	ds_read_b128 v[184:187], v235 offset:37888
	ds_read_b128 v[188:191], v235 offset:38912
	ds_read_b128 v[192:195], v235 offset:39936
	global_load_lds_dwordx4 v[222:223], off
	v_lshl_add_u64 v[222:223], s[14:15], 0, v[198:199]
	s_mov_b32 m0, s58
	s_nop 0
	global_load_lds_dwordx4 v[222:223], off
	s_waitcnt vmcnt(8)
	s_waitcnt lgkmcnt(0)
	s_barrier
	s_setprio 1
	s_waitcnt lgkmcnt(0)
	v_mfma_f32_16x16x32_bf16 v[128:131], v[132:135], v[164:167], v[128:131]
	v_mfma_f32_16x16x32_bf16 v[120:123], v[140:143], v[164:167], v[120:123]
	v_mfma_f32_16x16x32_bf16 v[112:115], v[132:135], v[172:175], v[112:115]
	v_mfma_f32_16x16x32_bf16 v[104:107], v[140:143], v[172:175], v[104:107]
	v_mfma_f32_16x16x32_bf16 v[96:99], v[132:135], v[180:183], v[96:99]
	v_mfma_f32_16x16x32_bf16 v[88:91], v[140:143], v[180:183], v[88:91]
	v_mfma_f32_16x16x32_bf16 v[80:83], v[132:135], v[188:191], v[80:83]
	v_mfma_f32_16x16x32_bf16 v[72:75], v[140:143], v[188:191], v[72:75]
	v_mfma_f32_16x16x32_bf16 v[128:131], v[136:139], v[168:171], v[128:131]
	v_mfma_f32_16x16x32_bf16 v[120:123], v[144:147], v[168:171], v[120:123]
	v_mfma_f32_16x16x32_bf16 v[112:115], v[136:139], v[176:179], v[112:115]
	v_mfma_f32_16x16x32_bf16 v[104:107], v[144:147], v[176:179], v[104:107]
	v_mfma_f32_16x16x32_bf16 v[96:99], v[136:139], v[184:187], v[96:99]
	v_mfma_f32_16x16x32_bf16 v[88:91], v[144:147], v[184:187], v[88:91]
	v_mfma_f32_16x16x32_bf16 v[80:83], v[136:139], v[192:195], v[80:83]
	v_mfma_f32_16x16x32_bf16 v[72:75], v[144:147], v[192:195], v[72:75]
	s_setprio 0
	s_setprio 1
	v_mfma_f32_16x16x32_bf16 v[124:127], v[148:151], v[164:167], v[124:127]
	v_mfma_f32_16x16x32_bf16 v[116:119], v[156:159], v[164:167], v[116:119]
	v_mfma_f32_16x16x32_bf16 v[108:111], v[148:151], v[172:175], v[108:111]
	v_mfma_f32_16x16x32_bf16 v[100:103], v[156:159], v[172:175], v[100:103]
	v_mfma_f32_16x16x32_bf16 v[92:95], v[148:151], v[180:183], v[92:95]
	v_mfma_f32_16x16x32_bf16 v[84:87], v[156:159], v[180:183], v[84:87]
	v_mfma_f32_16x16x32_bf16 v[76:79], v[148:151], v[188:191], v[76:79]
	v_mfma_f32_16x16x32_bf16 v[68:71], v[156:159], v[188:191], v[68:71]
	v_mfma_f32_16x16x32_bf16 v[124:127], v[152:155], v[168:171], v[124:127]
	v_mfma_f32_16x16x32_bf16 v[116:119], v[160:163], v[168:171], v[116:119]
	v_mfma_f32_16x16x32_bf16 v[108:111], v[152:155], v[176:179], v[108:111]
	v_mfma_f32_16x16x32_bf16 v[100:103], v[160:163], v[176:179], v[100:103]
	v_mfma_f32_16x16x32_bf16 v[92:95], v[152:155], v[184:187], v[92:95]
	v_mfma_f32_16x16x32_bf16 v[84:87], v[160:163], v[184:187], v[84:87]
	v_mfma_f32_16x16x32_bf16 v[76:79], v[152:155], v[192:195], v[76:79]
	v_mfma_f32_16x16x32_bf16 v[68:71], v[160:163], v[192:195], v[68:71]
	s_setprio 0
	s_barrier
; #define PG8_STAGE(bufoff, gbase, voff) do { _Pragma("unroll") for (int _i = 0; _i < 2; ++_i) \
;         __builtin_amdgcn_global_load_lds((const unsigned*)((const char*)(gbase) + (voff)[_i]), (LAS unsigned*)(lds + (bufoff) + ldsw + _i * 8192), 16, 0, 0); } while (0)
; #define PG8_LDA(dst, b, h) do { _Pragma("unroll") for (int m = 0; m < 4; ++m) _Pragma("unroll") for (int k = 0; k < 2; ++k) dst[m][k] = *(const LAS bf16x8*)(lds + PG8_SA(b, h) + aoff + m * 2048 + k * 1024); } while (0)
; #define PG8_MMA(ai, bj, At, Bt) do { __builtin_amdgcn_s_setprio(1); _Pragma("unroll") for (int m = 0; m < 4; ++m) _Pragma("unroll") for (int n = 0; n < 2; ++n) _Pragma("unroll") for (int k = 0; k < 2; ++k) \
;         acc[ai][bj][m][n] = __builtin_amdgcn_mfma_f32_16x16x32_bf16(Bt[n][k], At[m][k], acc[ai][bj][m][n], 0, 0, 0); __builtin_amdgcn_s_setprio(0); } while (0)
; #define PG8_WAIT_V(n) asm volatile("s_waitcnt vmcnt(" #n ")" ::: "memory")
; #define PG8_WAIT_L(n) asm volatile("s_waitcnt lgkmcnt(" #n ")" ::: "memory")
; #define PG8_BAR __builtin_amdgcn_s_barrier()
; #define PG8_SCHED __builtin_amdgcn_sched_barrier(0)
; __device__ __forceinline__ void gemm_phase(LAS unsigned char* lds, const Gemm g, const StaticOrder& S, const LAS Epi* Ep, const int tid) {
;     ...
;             PG8_WAIT_V(8); PG8_WAIT_L(0); PG8_BAR; PG8_MMA(0, 0, At, B0); PG8_MMA(0, 1, At, B1); PG8_BAR; PG8_SCHED;
;             PG8_LDA(At, 1, 1); PG8_STAGE(PG8_SB(1, 0), b3, voffB); PG8_STAGE(PG8_SB(1, 1), b3 + hstepB, voffB); PG8_STAGE(PG8_SA(1, 0), a3, voffA);
;             PG8_WAIT_V(8); PG8_WAIT_L(0); PG8_BAR; PG8_MMA(1, 0, At, B0); PG8_MMA(1, 1, At, B1); PG8_BAR; PG8_SCHED;
;         }
	s_add_i32 s14, s18, s85
	v_lshl_add_u64 v[210:211], v[210:211], 0, s[88:89]
	s_mov_b32 m0, s14
	ds_read_b128 v[164:167], v235 offset:49152
	ds_read_b128 v[168:171], v235 offset:50176
	ds_read_b128 v[172:175], v235 offset:51200
	ds_read_b128 v[176:179], v235 offset:52224
	ds_read_b128 v[180:183], v235 offset:53248
	ds_read_b128 v[184:187], v235 offset:54272
	ds_read_b128 v[188:191], v235 offset:55296
	ds_read_b128 v[192:195], v235 offset:56320
	global_load_lds_dwordx4 v[210:211], off
	v_lshl_add_u64 v[210:211], v[212:213], 0, s[88:89]
	s_add_i32 m0, s14, 0x2000
	s_add_i32 s14, s19, s85
	global_load_lds_dwordx4 v[210:211], off
	v_lshl_add_u64 v[210:211], v[214:215], 0, s[88:89]
	s_mov_b32 m0, s14
	s_nop 0
	global_load_lds_dwordx4 v[210:211], off
	v_lshl_add_u64 v[210:211], v[216:217], 0, s[88:89]
	s_add_i32 m0, s14, 0x2000
	s_nop 0
	global_load_lds_dwordx4 v[210:211], off
	v_lshl_add_u64 v[210:211], v[218:219], 0, s[88:89]
	s_mov_b32 m0, s59
	s_nop 0
	global_load_lds_dwordx4 v[210:211], off
	v_lshl_add_u64 v[210:211], v[220:221], 0, s[88:89]
	s_mov_b32 m0, s60
	s_nop 0
	global_load_lds_dwordx4 v[210:211], off
	s_waitcnt vmcnt(8)
	s_waitcnt lgkmcnt(0)
	s_barrier
	s_setprio 1
	s_waitcnt lgkmcnt(0)
	v_mfma_f32_16x16x32_bf16 v[64:67], v[132:135], v[164:167], v[64:67]
	v_mfma_f32_16x16x32_bf16 v[56:59], v[140:143], v[164:167], v[56:59]
	v_mfma_f32_16x16x32_bf16 v[48:51], v[132:135], v[172:175], v[48:51]
	v_mfma_f32_16x16x32_bf16 v[40:43], v[140:143], v[172:175], v[40:43]
	v_mfma_f32_16x16x32_bf16 v[32:35], v[132:135], v[180:183], v[32:35]
	v_mfma_f32_16x16x32_bf16 v[24:27], v[140:143], v[180:183], v[24:27]
	v_mfma_f32_16x16x32_bf16 v[16:19], v[132:135], v[188:191], v[16:19]
	v_mfma_f32_16x16x32_bf16 v[8:11], v[140:143], v[188:191], v[8:11]
	v_mfma_f32_16x16x32_bf16 v[64:67], v[136:139], v[168:171], v[64:67]
	v_mfma_f32_16x16x32_bf16 v[56:59], v[144:147], v[168:171], v[56:59]
	v_mfma_f32_16x16x32_bf16 v[48:51], v[136:139], v[176:179], v[48:51]
	v_mfma_f32_16x16x32_bf16 v[40:43], v[144:147], v[176:179], v[40:43]
	v_mfma_f32_16x16x32_bf16 v[32:35], v[136:139], v[184:187], v[32:35]
	v_mfma_f32_16x16x32_bf16 v[24:27], v[144:147], v[184:187], v[24:27]
	v_mfma_f32_16x16x32_bf16 v[16:19], v[136:139], v[192:195], v[16:19]
	v_mfma_f32_16x16x32_bf16 v[8:11], v[144:147], v[192:195], v[8:11]
	s_setprio 0
	s_setprio 1
	v_mfma_f32_16x16x32_bf16 v[60:63], v[148:151], v[164:167], v[60:63]
	v_mfma_f32_16x16x32_bf16 v[52:55], v[156:159], v[164:167], v[52:55]
	v_mfma_f32_16x16x32_bf16 v[44:47], v[148:151], v[172:175], v[44:47]
	v_mfma_f32_16x16x32_bf16 v[36:39], v[156:159], v[172:175], v[36:39]
	v_mfma_f32_16x16x32_bf16 v[28:31], v[148:151], v[180:183], v[28:31]
	v_mfma_f32_16x16x32_bf16 v[20:23], v[156:159], v[180:183], v[20:23]
	v_mfma_f32_16x16x32_bf16 v[12:15], v[148:151], v[188:191], v[12:15]
	v_mfma_f32_16x16x32_bf16 v[4:7], v[156:159], v[188:191], v[4:7]
	v_mfma_f32_16x16x32_bf16 v[60:63], v[152:155], v[168:171], v[60:63]
	v_mfma_f32_16x16x32_bf16 v[52:55], v[160:163], v[168:171], v[52:55]
	v_mfma_f32_16x16x32_bf16 v[44:47], v[152:155], v[176:179], v[44:47]
	v_mfma_f32_16x16x32_bf16 v[36:39], v[160:163], v[176:179], v[36:39]
	v_mfma_f32_16x16x32_bf16 v[28:31], v[152:155], v[184:187], v[28:31]
	v_mfma_f32_16x16x32_bf16 v[20:23], v[160:163], v[184:187], v[20:23]
	v_mfma_f32_16x16x32_bf16 v[12:15], v[152:155], v[192:195], v[12:15]
	v_mfma_f32_16x16x32_bf16 v[4:7], v[160:163], v[192:195], v[4:7]
	s_setprio 0
	s_barrier
	s_add_u32 s0, s0, 0x100
	s_addc_u32 s1, s1, 0
	s_add_u32 s3, s3, 0x100
	s_addc_u32 s16, s16, 0
	s_cmp_ge_u32 s17, s61
	s_mov_b32 s14, s17
	s_cbranch_scc0 .LBB0_407
	s_branch .Lpeel1_exit
	.p2alignl 6, 3212836864

; #define PG8_STAGE(bufoff, gbase, voff) do { _Pragma("unroll") for (int _i = 0; _i < 2; ++_i) \
;         __builtin_amdgcn_global_load_lds((const unsigned*)((const char*)(gbase) + (voff)[_i]), (LAS unsigned*)(lds + (bufoff) + ldsw + _i * 8192), 16, 0, 0); } while (0)
; #define PG8_LDA(dst, b, h) do { _Pragma("unroll") for (int m = 0; m < 4; ++m) _Pragma("unroll") for (int k = 0; k < 2; ++k) dst[m][k] = *(const LAS bf16x8*)(lds + PG8_SA(b, h) + aoff + m * 2048 + k * 1024); } while (0)
; #define PG8_LDB(dst, b, h) do { _Pragma("unroll") for (int n = 0; n < 2; ++n) _Pragma("unroll") for (int k = 0; k < 2; ++k) dst[n][k] = *(const LAS bf16x8*)(lds + PG8_SB(b, h) + boff + n * 2048 + k * 1024); } while (0)
; #define PG8_MMA(ai, bj, At, Bt) do { __builtin_amdgcn_s_setprio(1); _Pragma("unroll") for (int m = 0; m < 4; ++m) _Pragma("unroll") for (int n = 0; n < 2; ++n) _Pragma("unroll") for (int k = 0; k < 2; ++k) \
;         acc[ai][bj][m][n] = __builtin_amdgcn_mfma_f32_16x16x32_bf16(Bt[n][k], At[m][k], acc[ai][bj][m][n], 0, 0, 0); __builtin_amdgcn_s_setprio(0); } while (0)
; #define PG8_WAIT_V(n) asm volatile("s_waitcnt vmcnt(" #n ")" ::: "memory")
; #define PG8_WAIT_L(n) asm volatile("s_waitcnt lgkmcnt(" #n ")" ::: "memory")
; #define PG8_BAR __builtin_amdgcn_s_barrier()
; #define PG8_SCHED __builtin_amdgcn_sched_barrier(0)
; __device__ __forceinline__ void gemm_phase(LAS unsigned char* lds, const Gemm g, const StaticOrder& S, const LAS Epi* Ep, const int tid) {
;     ...
;         for (int t = 0; t < nt; t += 2) {
;             const bool last = (t == nt - 2);
;             const char* a1 = cA + (size_t)(t + 1) * kstep;
;             const char* a2 = last ? nA : cA + (size_t)(t + 2) * kstep; const char* b2 = last ? nB : cB + (size_t)(t + 2) * kstep;
;             const char* a3 = a2 + kstep; const char* b3 = b2 + kstep;
;             PG8_LDB(B0, 0, 0); PG8_LDB(B1, 0, 1); PG8_SCHED; PG8_LDA(At, 0, 0); PG8_STAGE(PG8_SA(1, 1), a1 + hstepA, voffA);
;             PG8_WAIT_V(8); PG8_WAIT_L(0); PG8_BAR; PG8_MMA(0, 0, At, B0); PG8_MMA(0, 1, At, B1); PG8_BAR; PG8_SCHED;
;             PG8_LDA(At, 0, 1); PG8_STAGE(PG8_SB(0, 0), b2, voffB); PG8_STAGE(PG8_SB(0, 1), b2 + hstepB, voffB); PG8_STAGE(PG8_SA(0, 0), a2, voffA);
;             PG8_WAIT_V(8); PG8_WAIT_L(0); PG8_BAR; PG8_MMA(1, 0, At, B0); PG8_MMA(1, 1, At, B1); PG8_BAR; PG8_SCHED;
.Lstag2_skip:
	s_add_i32 s48, s23, 2
	s_add_u32 s38, s0, 0x80
	s_addc_u32 s39, s1, 0
	s_add_i32 s49, 0, 0x10000
	s_cmp_eq_u32 s20, s23
	s_cselect_b32 s39, s35, s39
	s_cselect_b32 s38, s34, s38
	v_add_u32_e32 v0, s49, v247
	s_cselect_b32 s51, s37, s5
	s_cselect_b32 s50, s36, s3
	s_add_i32 s23, 0, 0x14000
	s_waitcnt lgkmcnt(0)
	ds_read_b128 v[130:133], v0
	ds_read_b128 v[134:137], v0 offset:1024
	ds_read_b128 v[138:141], v0 offset:2048
	ds_read_b128 v[142:145], v0 offset:3072
	v_add_u32_e32 v0, s23, v247
	ds_read_b128 v[146:149], v0
	ds_read_b128 v[150:153], v0 offset:1024
	ds_read_b128 v[154:157], v0 offset:2048
	ds_read_b128 v[158:161], v0 offset:3072
	v_lshl_add_u64 v[210:211], s[0:1], 0, v[206:207]
	s_add_i32 m0, s67, 0xc000
	ds_read_b128 v[162:165], v249
	ds_read_b128 v[166:169], v249 offset:1024
	ds_read_b128 v[170:173], v249 offset:2048
	ds_read_b128 v[174:177], v249 offset:3072
	ds_read_b128 v[178:181], v249 offset:4096
	ds_read_b128 v[182:185], v249 offset:5120
	ds_read_b128 v[186:189], v249 offset:6144
	ds_read_b128 v[190:193], v249 offset:7168
	global_load_lds_dwordx4 v[210:211], off
	v_lshl_add_u64 v[210:211], s[0:1], 0, v[208:209]
	s_add_i32 m0, s67, 0xe000
	s_nop 0
	global_load_lds_dwordx4 v[210:211], off
	s_waitcnt vmcnt(8)
	s_waitcnt lgkmcnt(0)
	s_barrier
	s_setprio 1
	s_waitcnt lgkmcnt(0)
	v_mfma_f32_16x16x32_bf16 v[126:129], v[130:133], v[162:165], 0
	v_mfma_f32_16x16x32_bf16 v[118:121], v[138:141], v[162:165], 0
	v_mfma_f32_16x16x32_bf16 v[110:113], v[130:133], v[170:173], 0
	v_mfma_f32_16x16x32_bf16 v[102:105], v[138:141], v[170:173], 0
	v_mfma_f32_16x16x32_bf16 v[94:97], v[130:133], v[178:181], 0
	v_mfma_f32_16x16x32_bf16 v[86:89], v[138:141], v[178:181], 0
	v_mfma_f32_16x16x32_bf16 v[78:81], v[130:133], v[186:189], 0
	v_mfma_f32_16x16x32_bf16 v[70:73], v[138:141], v[186:189], 0
	v_mfma_f32_16x16x32_bf16 v[126:129], v[134:137], v[166:169], v[126:129]
	v_mfma_f32_16x16x32_bf16 v[118:121], v[142:145], v[166:169], v[118:121]
	v_mfma_f32_16x16x32_bf16 v[110:113], v[134:137], v[174:177], v[110:113]
	v_mfma_f32_16x16x32_bf16 v[102:105], v[142:145], v[174:177], v[102:105]
	v_mfma_f32_16x16x32_bf16 v[94:97], v[134:137], v[182:185], v[94:97]
	v_mfma_f32_16x16x32_bf16 v[86:89], v[142:145], v[182:185], v[86:89]
	v_mfma_f32_16x16x32_bf16 v[78:81], v[134:137], v[190:193], v[78:81]
	v_mfma_f32_16x16x32_bf16 v[70:73], v[142:145], v[190:193], v[70:73]
	s_setprio 0
	s_setprio 1
	v_mfma_f32_16x16x32_bf16 v[122:125], v[146:149], v[162:165], 0
	v_mfma_f32_16x16x32_bf16 v[114:117], v[154:157], v[162:165], 0
	v_mfma_f32_16x16x32_bf16 v[106:109], v[146:149], v[170:173], 0
	v_mfma_f32_16x16x32_bf16 v[98:101], v[154:157], v[170:173], 0
	v_mfma_f32_16x16x32_bf16 v[90:93], v[146:149], v[178:181], 0
	v_mfma_f32_16x16x32_bf16 v[82:85], v[154:157], v[178:181], 0
	v_mfma_f32_16x16x32_bf16 v[74:77], v[146:149], v[186:189], 0
	v_mfma_f32_16x16x32_bf16 v[66:69], v[154:157], v[186:189], 0
	v_mfma_f32_16x16x32_bf16 v[122:125], v[150:153], v[166:169], v[122:125]
	v_mfma_f32_16x16x32_bf16 v[114:117], v[158:161], v[166:169], v[114:117]
	v_mfma_f32_16x16x32_bf16 v[106:109], v[150:153], v[174:177], v[106:109]
	v_mfma_f32_16x16x32_bf16 v[98:101], v[158:161], v[174:177], v[98:101]
	v_mfma_f32_16x16x32_bf16 v[90:93], v[150:153], v[182:185], v[90:93]
	v_mfma_f32_16x16x32_bf16 v[82:85], v[158:161], v[182:185], v[82:85]
	v_mfma_f32_16x16x32_bf16 v[74:77], v[150:153], v[190:193], v[74:77]
	v_mfma_f32_16x16x32_bf16 v[66:69], v[158:161], v[190:193], v[66:69]
	s_setprio 0
	s_barrier
	s_add_i32 s49, s49, s2
	v_lshl_add_u64 v[210:211], s[50:51], 0, v[198:199]
	s_mov_b32 m0, s49
	ds_read_b128 v[162:165], v249 offset:16384
	ds_read_b128 v[166:169], v249 offset:17408
	ds_read_b128 v[170:173], v249 offset:18432
	ds_read_b128 v[174:177], v249 offset:19456
	ds_read_b128 v[178:181], v249 offset:20480
	ds_read_b128 v[182:185], v249 offset:21504
	ds_read_b128 v[186:189], v249 offset:22528
	ds_read_b128 v[190:193], v249 offset:23552
	global_load_lds_dwordx4 v[210:211], off
	s_add_i32 m0, s49, 0x2000
	v_lshl_add_u64 v[212:213], s[50:51], 0, v[202:203]
	s_add_u32 s50, s50, s74
	s_addc_u32 s51, s51, 0
	s_add_i32 s23, s23, s2
	global_load_lds_dwordx4 v[212:213], off
	v_lshl_add_u64 v[214:215], s[50:51], 0, v[198:199]
	s_mov_b32 m0, s23
	v_lshl_add_u64 v[216:217], s[50:51], 0, v[202:203]
	global_load_lds_dwordx4 v[214:215], off
	s_add_i32 m0, s23, 0x2000
	v_lshl_add_u64 v[218:219], s[38:39], 0, v[196:197]
	global_load_lds_dwordx4 v[216:217], off
	s_mov_b32 m0, s67
	v_lshl_add_u64 v[220:221], s[38:39], 0, v[200:201]
	global_load_lds_dwordx4 v[218:219], off
	s_mov_b32 m0, s7
	s_nop 0
	global_load_lds_dwordx4 v[220:221], off
	s_waitcnt vmcnt(8)
	s_waitcnt lgkmcnt(0)
	s_barrier
; #define PG8_STAGE(bufoff, gbase, voff) do { _Pragma("unroll") for (int _i = 0; _i < 2; ++_i) \
;         __builtin_amdgcn_global_load_lds((const unsigned*)((const char*)(gbase) + (voff)[_i]), (LAS unsigned*)(lds + (bufoff) + ldsw + _i * 8192), 16, 0, 0); } while (0)
; #define PG8_LDA(dst, b, h) do { _Pragma("unroll") for (int m = 0; m < 4; ++m) _Pragma("unroll") for (int k = 0; k < 2; ++k) dst[m][k] = *(const LAS bf16x8*)(lds + PG8_SA(b, h) + aoff + m * 2048 + k * 1024); } while (0)
; #define PG8_LDB(dst, b, h) do { _Pragma("unroll") for (int n = 0; n < 2; ++n) _Pragma("unroll") for (int k = 0; k < 2; ++k) dst[n][k] = *(const LAS bf16x8*)(lds + PG8_SB(b, h) + boff + n * 2048 + k * 1024); } while (0)
; #define PG8_MMA(ai, bj, At, Bt) do { __builtin_amdgcn_s_setprio(1); _Pragma("unroll") for (int m = 0; m < 4; ++m) _Pragma("unroll") for (int n = 0; n < 2; ++n) _Pragma("unroll") for (int k = 0; k < 2; ++k) \
;         acc[ai][bj][m][n] = __builtin_amdgcn_mfma_f32_16x16x32_bf16(Bt[n][k], At[m][k], acc[ai][bj][m][n], 0, 0, 0); __builtin_amdgcn_s_setprio(0); } while (0)
; #define PG8_WAIT_V(n) asm volatile("s_waitcnt vmcnt(" #n ")" ::: "memory")
; #define PG8_WAIT_L(n) asm volatile("s_waitcnt lgkmcnt(" #n ")" ::: "memory")
; #define PG8_BAR __builtin_amdgcn_s_barrier()
; #define PG8_SCHED __builtin_amdgcn_sched_barrier(0)
; __device__ __forceinline__ void gemm_phase(LAS unsigned char* lds, const Gemm g, const StaticOrder& S, const LAS Epi* Ep, const int tid) {
;     ...
;             PG8_WAIT_V(8); PG8_WAIT_L(0); PG8_BAR; PG8_MMA(1, 0, At, B0); PG8_MMA(1, 1, At, B1); PG8_BAR; PG8_SCHED;
;             PG8_LDB(B0, 1, 0); PG8_LDB(B1, 1, 1); PG8_SCHED; PG8_LDA(At, 1, 0); PG8_STAGE(PG8_SA(0, 1), a2 + hstepA, voffA);
;             PG8_WAIT_V(8); PG8_WAIT_L(0); PG8_BAR; PG8_MMA(0, 0, At, B0); PG8_MMA(0, 1, At, B1); PG8_BAR; PG8_SCHED;
	s_setprio 1
	s_waitcnt lgkmcnt(0)
	v_mfma_f32_16x16x32_bf16 v[62:65], v[130:133], v[162:165], 0
	v_mfma_f32_16x16x32_bf16 v[54:57], v[138:141], v[162:165], 0
	v_mfma_f32_16x16x32_bf16 v[46:49], v[130:133], v[170:173], 0
	v_mfma_f32_16x16x32_bf16 v[38:41], v[138:141], v[170:173], 0
	v_mfma_f32_16x16x32_bf16 v[30:33], v[130:133], v[178:181], 0
	v_mfma_f32_16x16x32_bf16 v[22:25], v[138:141], v[178:181], 0
	v_mfma_f32_16x16x32_bf16 v[14:17], v[130:133], v[186:189], 0
	v_mfma_f32_16x16x32_bf16 v[6:9], v[138:141], v[186:189], 0
	v_mfma_f32_16x16x32_bf16 v[62:65], v[134:137], v[166:169], v[62:65]
	v_mfma_f32_16x16x32_bf16 v[54:57], v[142:145], v[166:169], v[54:57]
	v_mfma_f32_16x16x32_bf16 v[46:49], v[134:137], v[174:177], v[46:49]
	v_mfma_f32_16x16x32_bf16 v[38:41], v[142:145], v[174:177], v[38:41]
	v_mfma_f32_16x16x32_bf16 v[30:33], v[134:137], v[182:185], v[30:33]
	v_mfma_f32_16x16x32_bf16 v[22:25], v[142:145], v[182:185], v[22:25]
	v_mfma_f32_16x16x32_bf16 v[14:17], v[134:137], v[190:193], v[14:17]
	v_mfma_f32_16x16x32_bf16 v[6:9], v[142:145], v[190:193], v[6:9]
	s_setprio 0
	s_setprio 1
	v_mfma_f32_16x16x32_bf16 v[58:61], v[146:149], v[162:165], 0
	v_mfma_f32_16x16x32_bf16 v[50:53], v[154:157], v[162:165], 0
	v_mfma_f32_16x16x32_bf16 v[42:45], v[146:149], v[170:173], 0
	v_mfma_f32_16x16x32_bf16 v[34:37], v[154:157], v[170:173], 0
	v_mfma_f32_16x16x32_bf16 v[26:29], v[146:149], v[178:181], 0
	v_mfma_f32_16x16x32_bf16 v[18:21], v[154:157], v[178:181], 0
	v_mfma_f32_16x16x32_bf16 v[10:13], v[146:149], v[186:189], 0
	v_mfma_f32_16x16x32_bf16 v[2:5], v[154:157], v[186:189], 0
	v_mfma_f32_16x16x32_bf16 v[58:61], v[150:153], v[166:169], v[58:61]
	v_mfma_f32_16x16x32_bf16 v[50:53], v[158:161], v[166:169], v[50:53]
	v_mfma_f32_16x16x32_bf16 v[42:45], v[150:153], v[174:177], v[42:45]
	v_mfma_f32_16x16x32_bf16 v[34:37], v[158:161], v[174:177], v[34:37]
	v_mfma_f32_16x16x32_bf16 v[26:29], v[150:153], v[182:185], v[26:29]
	v_mfma_f32_16x16x32_bf16 v[18:21], v[158:161], v[182:185], v[18:21]
	v_mfma_f32_16x16x32_bf16 v[10:13], v[150:153], v[190:193], v[10:13]
	v_mfma_f32_16x16x32_bf16 v[2:5], v[158:161], v[190:193], v[2:5]
	s_setprio 0
	s_barrier
	s_add_i32 s23, 0, 0x18000
	v_add_u32_e32 v0, s23, v247
	s_add_i32 s49, 0, 0x1c000
	ds_read_b128 v[130:133], v0
	ds_read_b128 v[134:137], v0 offset:1024
	ds_read_b128 v[138:141], v0 offset:2048
	ds_read_b128 v[142:145], v0 offset:3072
	v_add_u32_e32 v0, s49, v247
	ds_read_b128 v[146:149], v0
	ds_read_b128 v[150:153], v0 offset:1024
	ds_read_b128 v[154:157], v0 offset:2048
	ds_read_b128 v[158:161], v0 offset:3072
	s_add_u32 s38, s38, s86
	s_addc_u32 s39, s39, 0
	s_mov_b32 m0, s14
	v_lshl_add_u64 v[222:223], s[38:39], 0, v[196:197]
	ds_read_b128 v[162:165], v249 offset:32768
	ds_read_b128 v[166:169], v249 offset:33792
	ds_read_b128 v[170:173], v249 offset:34816
	ds_read_b128 v[174:177], v249 offset:35840
	ds_read_b128 v[178:181], v249 offset:36864
	ds_read_b128 v[182:185], v249 offset:37888
	ds_read_b128 v[186:189], v249 offset:38912
	ds_read_b128 v[190:193], v249 offset:39936
	global_load_lds_dwordx4 v[222:223], off
	v_lshl_add_u64 v[222:223], s[38:39], 0, v[200:201]
	s_mov_b32 m0, s15
	s_nop 0
	global_load_lds_dwordx4 v[222:223], off
	s_waitcnt vmcnt(8)
	s_waitcnt lgkmcnt(0)
	s_barrier
	s_setprio 1
	s_waitcnt lgkmcnt(0)
	v_mfma_f32_16x16x32_bf16 v[126:129], v[130:133], v[162:165], v[126:129]
	v_mfma_f32_16x16x32_bf16 v[118:121], v[138:141], v[162:165], v[118:121]
	v_mfma_f32_16x16x32_bf16 v[110:113], v[130:133], v[170:173], v[110:113]
	v_mfma_f32_16x16x32_bf16 v[102:105], v[138:141], v[170:173], v[102:105]
	v_mfma_f32_16x16x32_bf16 v[94:97], v[130:133], v[178:181], v[94:97]
	v_mfma_f32_16x16x32_bf16 v[86:89], v[138:141], v[178:181], v[86:89]
	v_mfma_f32_16x16x32_bf16 v[78:81], v[130:133], v[186:189], v[78:81]
	v_mfma_f32_16x16x32_bf16 v[70:73], v[138:141], v[186:189], v[70:73]
	v_mfma_f32_16x16x32_bf16 v[126:129], v[134:137], v[166:169], v[126:129]
	v_mfma_f32_16x16x32_bf16 v[118:121], v[142:145], v[166:169], v[118:121]
	v_mfma_f32_16x16x32_bf16 v[110:113], v[134:137], v[174:177], v[110:113]
	v_mfma_f32_16x16x32_bf16 v[102:105], v[142:145], v[174:177], v[102:105]
	v_mfma_f32_16x16x32_bf16 v[94:97], v[134:137], v[182:185], v[94:97]
	v_mfma_f32_16x16x32_bf16 v[86:89], v[142:145], v[182:185], v[86:89]
	v_mfma_f32_16x16x32_bf16 v[78:81], v[134:137], v[190:193], v[78:81]
	v_mfma_f32_16x16x32_bf16 v[70:73], v[142:145], v[190:193], v[70:73]
	s_setprio 0
	s_setprio 1
	v_mfma_f32_16x16x32_bf16 v[122:125], v[146:149], v[162:165], v[122:125]
	v_mfma_f32_16x16x32_bf16 v[114:117], v[154:157], v[162:165], v[114:117]
	v_mfma_f32_16x16x32_bf16 v[106:109], v[146:149], v[170:173], v[106:109]
	v_mfma_f32_16x16x32_bf16 v[98:101], v[154:157], v[170:173], v[98:101]
	v_mfma_f32_16x16x32_bf16 v[90:93], v[146:149], v[178:181], v[90:93]
	v_mfma_f32_16x16x32_bf16 v[82:85], v[154:157], v[178:181], v[82:85]
	v_mfma_f32_16x16x32_bf16 v[74:77], v[146:149], v[186:189], v[74:77]
	v_mfma_f32_16x16x32_bf16 v[66:69], v[154:157], v[186:189], v[66:69]
	v_mfma_f32_16x16x32_bf16 v[122:125], v[150:153], v[166:169], v[122:125]
	v_mfma_f32_16x16x32_bf16 v[114:117], v[158:161], v[166:169], v[114:117]
	v_mfma_f32_16x16x32_bf16 v[106:109], v[150:153], v[174:177], v[106:109]
	v_mfma_f32_16x16x32_bf16 v[98:101], v[158:161], v[174:177], v[98:101]
	v_mfma_f32_16x16x32_bf16 v[90:93], v[150:153], v[182:185], v[90:93]
	v_mfma_f32_16x16x32_bf16 v[82:85], v[158:161], v[182:185], v[82:85]
	v_mfma_f32_16x16x32_bf16 v[74:77], v[150:153], v[190:193], v[74:77]
	v_mfma_f32_16x16x32_bf16 v[66:69], v[158:161], v[190:193], v[66:69]
	s_setprio 0
	s_barrier
; #define PG8_STAGE(bufoff, gbase, voff) do { _Pragma("unroll") for (int _i = 0; _i < 2; ++_i) \
;         __builtin_amdgcn_global_load_lds((const unsigned*)((const char*)(gbase) + (voff)[_i]), (LAS unsigned*)(lds + (bufoff) + ldsw + _i * 8192), 16, 0, 0); } while (0)
; #define PG8_LDA(dst, b, h) do { _Pragma("unroll") for (int m = 0; m < 4; ++m) _Pragma("unroll") for (int k = 0; k < 2; ++k) dst[m][k] = *(const LAS bf16x8*)(lds + PG8_SA(b, h) + aoff + m * 2048 + k * 1024); } while (0)
; #define PG8_MMA(ai, bj, At, Bt) do { __builtin_amdgcn_s_setprio(1); _Pragma("unroll") for (int m = 0; m < 4; ++m) _Pragma("unroll") for (int n = 0; n < 2; ++n) _Pragma("unroll") for (int k = 0; k < 2; ++k) \
;         acc[ai][bj][m][n] = __builtin_amdgcn_mfma_f32_16x16x32_bf16(Bt[n][k], At[m][k], acc[ai][bj][m][n], 0, 0, 0); __builtin_amdgcn_s_setprio(0); } while (0)
; #define PG8_WAIT_V(n) asm volatile("s_waitcnt vmcnt(" #n ")" ::: "memory")
; #define PG8_WAIT_L(n) asm volatile("s_waitcnt lgkmcnt(" #n ")" ::: "memory")
; #define PG8_BAR __builtin_amdgcn_s_barrier()
; #define PG8_SCHED __builtin_amdgcn_sched_barrier(0)
; __device__ __forceinline__ void gemm_phase(LAS unsigned char* lds, const Gemm g, const StaticOrder& S, const LAS Epi* Ep, const int tid) {
;     ...
;             PG8_WAIT_V(8); PG8_WAIT_L(0); PG8_BAR; PG8_MMA(0, 0, At, B0); PG8_MMA(0, 1, At, B1); PG8_BAR; PG8_SCHED;
;             PG8_LDA(At, 1, 1); PG8_STAGE(PG8_SB(1, 0), b3, voffB); PG8_STAGE(PG8_SB(1, 1), b3 + hstepB, voffB); PG8_STAGE(PG8_SA(1, 0), a3, voffA);
;             PG8_WAIT_V(8); PG8_WAIT_L(0); PG8_BAR; PG8_MMA(1, 0, At, B0); PG8_MMA(1, 1, At, B1); PG8_BAR; PG8_SCHED;
;         }
	s_add_i32 s23, s23, s2
	v_lshl_add_u64 v[210:211], v[210:211], 0, s[88:89]
	s_mov_b32 m0, s23
	ds_read_b128 v[162:165], v249 offset:49152
	ds_read_b128 v[166:169], v249 offset:50176
	ds_read_b128 v[170:173], v249 offset:51200
	ds_read_b128 v[174:177], v249 offset:52224
	ds_read_b128 v[178:181], v249 offset:53248
	ds_read_b128 v[182:185], v249 offset:54272
	ds_read_b128 v[186:189], v249 offset:55296
	ds_read_b128 v[190:193], v249 offset:56320
	global_load_lds_dwordx4 v[210:211], off
	v_lshl_add_u64 v[210:211], v[212:213], 0, s[88:89]
	s_add_i32 m0, s23, 0x2000
	s_add_i32 s23, s49, s2
	global_load_lds_dwordx4 v[210:211], off
	v_lshl_add_u64 v[210:211], v[214:215], 0, s[88:89]
	s_mov_b32 m0, s23
	s_nop 0
	global_load_lds_dwordx4 v[210:211], off
	v_lshl_add_u64 v[210:211], v[216:217], 0, s[88:89]
	s_add_i32 m0, s23, 0x2000
	s_nop 0
	global_load_lds_dwordx4 v[210:211], off
	v_lshl_add_u64 v[210:211], v[218:219], 0, s[88:89]
	s_mov_b32 m0, s10
	s_nop 0
	global_load_lds_dwordx4 v[210:211], off
	v_lshl_add_u64 v[210:211], v[220:221], 0, s[88:89]
	s_mov_b32 m0, s11
	s_nop 0
	global_load_lds_dwordx4 v[210:211], off
	s_waitcnt vmcnt(8)
	s_waitcnt lgkmcnt(0)
	s_barrier
	s_setprio 1
	s_waitcnt lgkmcnt(0)
	v_mfma_f32_16x16x32_bf16 v[62:65], v[130:133], v[162:165], v[62:65]
	v_mfma_f32_16x16x32_bf16 v[54:57], v[138:141], v[162:165], v[54:57]
	v_mfma_f32_16x16x32_bf16 v[46:49], v[130:133], v[170:173], v[46:49]
	v_mfma_f32_16x16x32_bf16 v[38:41], v[138:141], v[170:173], v[38:41]
	v_mfma_f32_16x16x32_bf16 v[30:33], v[130:133], v[178:181], v[30:33]
	v_mfma_f32_16x16x32_bf16 v[22:25], v[138:141], v[178:181], v[22:25]
	v_mfma_f32_16x16x32_bf16 v[14:17], v[130:133], v[186:189], v[14:17]
	v_mfma_f32_16x16x32_bf16 v[6:9], v[138:141], v[186:189], v[6:9]
	v_mfma_f32_16x16x32_bf16 v[62:65], v[134:137], v[166:169], v[62:65]
	v_mfma_f32_16x16x32_bf16 v[54:57], v[142:145], v[166:169], v[54:57]
	v_mfma_f32_16x16x32_bf16 v[46:49], v[134:137], v[174:177], v[46:49]
	v_mfma_f32_16x16x32_bf16 v[38:41], v[142:145], v[174:177], v[38:41]
	v_mfma_f32_16x16x32_bf16 v[30:33], v[134:137], v[182:185], v[30:33]
	v_mfma_f32_16x16x32_bf16 v[22:25], v[142:145], v[182:185], v[22:25]
	v_mfma_f32_16x16x32_bf16 v[14:17], v[134:137], v[190:193], v[14:17]
	v_mfma_f32_16x16x32_bf16 v[6:9], v[142:145], v[190:193], v[6:9]
	s_setprio 0
	s_setprio 1
	v_mfma_f32_16x16x32_bf16 v[58:61], v[146:149], v[162:165], v[58:61]
	v_mfma_f32_16x16x32_bf16 v[50:53], v[154:157], v[162:165], v[50:53]
	v_mfma_f32_16x16x32_bf16 v[42:45], v[146:149], v[170:173], v[42:45]
	v_mfma_f32_16x16x32_bf16 v[34:37], v[154:157], v[170:173], v[34:37]
	v_mfma_f32_16x16x32_bf16 v[26:29], v[146:149], v[178:181], v[26:29]
	v_mfma_f32_16x16x32_bf16 v[18:21], v[154:157], v[178:181], v[18:21]
	v_mfma_f32_16x16x32_bf16 v[10:13], v[146:149], v[186:189], v[10:13]
	v_mfma_f32_16x16x32_bf16 v[2:5], v[154:157], v[186:189], v[2:5]
	v_mfma_f32_16x16x32_bf16 v[58:61], v[150:153], v[166:169], v[58:61]
	v_mfma_f32_16x16x32_bf16 v[50:53], v[158:161], v[166:169], v[50:53]
	v_mfma_f32_16x16x32_bf16 v[42:45], v[150:153], v[174:177], v[42:45]
	v_mfma_f32_16x16x32_bf16 v[34:37], v[158:161], v[174:177], v[34:37]
	v_mfma_f32_16x16x32_bf16 v[26:29], v[150:153], v[182:185], v[26:29]
	v_mfma_f32_16x16x32_bf16 v[18:21], v[158:161], v[182:185], v[18:21]
	v_mfma_f32_16x16x32_bf16 v[10:13], v[150:153], v[190:193], v[10:13]
	v_mfma_f32_16x16x32_bf16 v[2:5], v[158:161], v[190:193], v[2:5]
	s_setprio 0
	s_barrier
	s_add_u32 s0, s0, 0x100
	s_addc_u32 s1, s1, 0
	s_add_u32 s3, s3, 0x100
	s_addc_u32 s5, s5, 0
	s_cmp_ge_u32 s48, s16
	s_mov_b32 s23, s48
	s_cbranch_scc0 .LBB0_1434
	s_branch .Lpeel2_exit
	.p2alignl 6, 3212836864

; #define PG8_STAGE(bufoff, gbase, voff) do { _Pragma("unroll") for (int _i = 0; _i < 2; ++_i) \
;         __builtin_amdgcn_global_load_lds((const unsigned*)((const char*)(gbase) + (voff)[_i]), (LAS unsigned*)(lds + (bufoff) + ldsw + _i * 8192), 16, 0, 0); } while (0)
; #define PG8_LDA(dst, b, h) do { _Pragma("unroll") for (int m = 0; m < 4; ++m) _Pragma("unroll") for (int k = 0; k < 2; ++k) dst[m][k] = *(const LAS bf16x8*)(lds + PG8_SA(b, h) + aoff + m * 2048 + k * 1024); } while (0)
; #define PG8_LDB(dst, b, h) do { _Pragma("unroll") for (int n = 0; n < 2; ++n) _Pragma("unroll") for (int k = 0; k < 2; ++k) dst[n][k] = *(const LAS bf16x8*)(lds + PG8_SB(b, h) + boff + n * 2048 + k * 1024); } while (0)
; #define PG8_MMA(ai, bj, At, Bt) do { __builtin_amdgcn_s_setprio(1); _Pragma("unroll") for (int m = 0; m < 4; ++m) _Pragma("unroll") for (int n = 0; n < 2; ++n) _Pragma("unroll") for (int k = 0; k < 2; ++k) \
;         acc[ai][bj][m][n] = __builtin_amdgcn_mfma_f32_16x16x32_bf16(Bt[n][k], At[m][k], acc[ai][bj][m][n], 0, 0, 0); __builtin_amdgcn_s_setprio(0); } while (0)
; #define PG8_WAIT_V(n) asm volatile("s_waitcnt vmcnt(" #n ")" ::: "memory")
; #define PG8_WAIT_L(n) asm volatile("s_waitcnt lgkmcnt(" #n ")" ::: "memory")
; #define PG8_BAR __builtin_amdgcn_s_barrier()
; #define PG8_SCHED __builtin_amdgcn_sched_barrier(0)
; __device__ __forceinline__ void gemm_phase(LAS unsigned char* lds, const Gemm g, const StaticOrder& S, const LAS Epi* Ep, const int tid) {
;     ...
;         for (int t = 0; t < nt; t += 2) {
;             const bool last = (t == nt - 2);
;             const char* a1 = cA + (size_t)(t + 1) * kstep;
;             const char* a2 = last ? nA : cA + (size_t)(t + 2) * kstep; const char* b2 = last ? nB : cB + (size_t)(t + 2) * kstep;
;             const char* a3 = a2 + kstep; const char* b3 = b2 + kstep;
;             PG8_LDB(B0, 0, 0); PG8_LDB(B1, 0, 1); PG8_SCHED; PG8_LDA(At, 0, 0); PG8_STAGE(PG8_SA(1, 1), a1 + hstepA, voffA);
;             PG8_WAIT_V(8); PG8_WAIT_L(0); PG8_BAR; PG8_MMA(0, 0, At, B0); PG8_MMA(0, 1, At, B1); PG8_BAR; PG8_SCHED;
;             PG8_LDA(At, 0, 1); PG8_STAGE(PG8_SB(0, 0), b2, voffB); PG8_STAGE(PG8_SB(0, 1), b2 + hstepB, voffB); PG8_STAGE(PG8_SA(0, 0), a2, voffA);
;             PG8_WAIT_V(8); PG8_WAIT_L(0); PG8_BAR; PG8_MMA(1, 0, At, B0); PG8_MMA(1, 1, At, B1); PG8_BAR; PG8_SCHED;
.Lstag3_skip:
	s_add_i32 s13, s10, 2
	s_add_u32 s14, s0, 0x80
	s_addc_u32 s11, s1, 0
	s_add_i32 s16, 0, 0x10000
	s_cmp_eq_u32 s68, s10
	s_cselect_b32 s11, s7, s11
	s_cselect_b32 s10, s6, s14
	v_add_u32_e32 v2, s16, v230
	s_cselect_b32 s15, s9, s12
	s_cselect_b32 s14, s8, s3
	s_add_i32 s17, 0, 0x14000
	s_waitcnt lgkmcnt(0)
	ds_read_b128 v[132:135], v2
	ds_read_b128 v[136:139], v2 offset:1024
	ds_read_b128 v[140:143], v2 offset:2048
	ds_read_b128 v[144:147], v2 offset:3072
	v_add_u32_e32 v2, s17, v230
	ds_read_b128 v[148:151], v2
	ds_read_b128 v[152:155], v2 offset:1024
	ds_read_b128 v[156:159], v2 offset:2048
	ds_read_b128 v[160:163], v2 offset:3072
	v_lshl_add_u64 v[210:211], s[0:1], 0, v[206:207]
	s_add_i32 m0, s87, 0xc000
	ds_read_b128 v[164:167], v232
	ds_read_b128 v[168:171], v232 offset:1024
	ds_read_b128 v[172:175], v232 offset:2048
	ds_read_b128 v[176:179], v232 offset:3072
	ds_read_b128 v[180:183], v232 offset:4096
	ds_read_b128 v[184:187], v232 offset:5120
	ds_read_b128 v[188:191], v232 offset:6144
	ds_read_b128 v[192:195], v232 offset:7168
	global_load_lds_dwordx4 v[210:211], off
	v_lshl_add_u64 v[210:211], s[0:1], 0, v[208:209]
	s_add_i32 m0, s87, 0xe000
	s_nop 0
	global_load_lds_dwordx4 v[210:211], off
	s_waitcnt vmcnt(8)
	s_waitcnt lgkmcnt(0)
	s_barrier
	s_setprio 1
	s_waitcnt lgkmcnt(0)
	v_mfma_f32_16x16x32_bf16 v[128:131], v[132:135], v[164:167], 0
	v_mfma_f32_16x16x32_bf16 v[120:123], v[140:143], v[164:167], 0
	v_mfma_f32_16x16x32_bf16 v[112:115], v[132:135], v[172:175], 0
	v_mfma_f32_16x16x32_bf16 v[104:107], v[140:143], v[172:175], 0
	v_mfma_f32_16x16x32_bf16 v[96:99], v[132:135], v[180:183], 0
	v_mfma_f32_16x16x32_bf16 v[88:91], v[140:143], v[180:183], 0
	v_mfma_f32_16x16x32_bf16 v[80:83], v[132:135], v[188:191], 0
	v_mfma_f32_16x16x32_bf16 v[72:75], v[140:143], v[188:191], 0
	v_mfma_f32_16x16x32_bf16 v[128:131], v[136:139], v[168:171], v[128:131]
	v_mfma_f32_16x16x32_bf16 v[120:123], v[144:147], v[168:171], v[120:123]
	v_mfma_f32_16x16x32_bf16 v[112:115], v[136:139], v[176:179], v[112:115]
	v_mfma_f32_16x16x32_bf16 v[104:107], v[144:147], v[176:179], v[104:107]
	v_mfma_f32_16x16x32_bf16 v[96:99], v[136:139], v[184:187], v[96:99]
	v_mfma_f32_16x16x32_bf16 v[88:91], v[144:147], v[184:187], v[88:91]
	v_mfma_f32_16x16x32_bf16 v[80:83], v[136:139], v[192:195], v[80:83]
	v_mfma_f32_16x16x32_bf16 v[72:75], v[144:147], v[192:195], v[72:75]
	s_setprio 0
	s_setprio 1
	v_mfma_f32_16x16x32_bf16 v[124:127], v[148:151], v[164:167], 0
	v_mfma_f32_16x16x32_bf16 v[116:119], v[156:159], v[164:167], 0
	v_mfma_f32_16x16x32_bf16 v[108:111], v[148:151], v[172:175], 0
	v_mfma_f32_16x16x32_bf16 v[100:103], v[156:159], v[172:175], 0
	v_mfma_f32_16x16x32_bf16 v[92:95], v[148:151], v[180:183], 0
	v_mfma_f32_16x16x32_bf16 v[84:87], v[156:159], v[180:183], 0
	v_mfma_f32_16x16x32_bf16 v[76:79], v[148:151], v[188:191], 0
	v_mfma_f32_16x16x32_bf16 v[68:71], v[156:159], v[188:191], 0
	v_mfma_f32_16x16x32_bf16 v[124:127], v[152:155], v[168:171], v[124:127]
	v_mfma_f32_16x16x32_bf16 v[116:119], v[160:163], v[168:171], v[116:119]
	v_mfma_f32_16x16x32_bf16 v[108:111], v[152:155], v[176:179], v[108:111]
	v_mfma_f32_16x16x32_bf16 v[100:103], v[160:163], v[176:179], v[100:103]
	v_mfma_f32_16x16x32_bf16 v[92:95], v[152:155], v[184:187], v[92:95]
	v_mfma_f32_16x16x32_bf16 v[84:87], v[160:163], v[184:187], v[84:87]
	v_mfma_f32_16x16x32_bf16 v[76:79], v[152:155], v[192:195], v[76:79]
	v_mfma_f32_16x16x32_bf16 v[68:71], v[160:163], v[192:195], v[68:71]
	s_setprio 0
	s_barrier
	s_add_i32 s16, s16, s86
	v_lshl_add_u64 v[210:211], s[14:15], 0, v[196:197]
	s_mov_b32 m0, s16
	ds_read_b128 v[164:167], v232 offset:16384
	ds_read_b128 v[168:171], v232 offset:17408
	ds_read_b128 v[172:175], v232 offset:18432
	ds_read_b128 v[176:179], v232 offset:19456
	ds_read_b128 v[180:183], v232 offset:20480
	ds_read_b128 v[184:187], v232 offset:21504
	ds_read_b128 v[188:191], v232 offset:22528
	ds_read_b128 v[192:195], v232 offset:23552
	global_load_lds_dwordx4 v[210:211], off
	s_add_i32 m0, s16, 0x2000
	v_lshl_add_u64 v[212:213], s[14:15], 0, v[200:201]
	s_add_u32 s14, s14, s58
	s_addc_u32 s15, s15, 0
	s_add_i32 s16, s17, s86
	global_load_lds_dwordx4 v[212:213], off
	v_lshl_add_u64 v[214:215], s[14:15], 0, v[196:197]
	s_mov_b32 m0, s16
	v_lshl_add_u64 v[216:217], s[14:15], 0, v[200:201]
	global_load_lds_dwordx4 v[214:215], off
	s_add_i32 m0, s16, 0x2000
	v_lshl_add_u64 v[218:219], s[10:11], 0, v[0:1]
	global_load_lds_dwordx4 v[216:217], off
	s_mov_b32 m0, s87
	v_lshl_add_u64 v[220:221], s[10:11], 0, v[198:199]
	global_load_lds_dwordx4 v[218:219], off
	s_mov_b32 m0, s38
	s_nop 0
	global_load_lds_dwordx4 v[220:221], off
	s_waitcnt vmcnt(8)
	s_waitcnt lgkmcnt(0)
	s_barrier
; #define PG8_STAGE(bufoff, gbase, voff) do { _Pragma("unroll") for (int _i = 0; _i < 2; ++_i) \
;         __builtin_amdgcn_global_load_lds((const unsigned*)((const char*)(gbase) + (voff)[_i]), (LAS unsigned*)(lds + (bufoff) + ldsw + _i * 8192), 16, 0, 0); } while (0)
; #define PG8_LDA(dst, b, h) do { _Pragma("unroll") for (int m = 0; m < 4; ++m) _Pragma("unroll") for (int k = 0; k < 2; ++k) dst[m][k] = *(const LAS bf16x8*)(lds + PG8_SA(b, h) + aoff + m * 2048 + k * 1024); } while (0)
; #define PG8_LDB(dst, b, h) do { _Pragma("unroll") for (int n = 0; n < 2; ++n) _Pragma("unroll") for (int k = 0; k < 2; ++k) dst[n][k] = *(const LAS bf16x8*)(lds + PG8_SB(b, h) + boff + n * 2048 + k * 1024); } while (0)
; #define PG8_MMA(ai, bj, At, Bt) do { __builtin_amdgcn_s_setprio(1); _Pragma("unroll") for (int m = 0; m < 4; ++m) _Pragma("unroll") for (int n = 0; n < 2; ++n) _Pragma("unroll") for (int k = 0; k < 2; ++k) \
;         acc[ai][bj][m][n] = __builtin_amdgcn_mfma_f32_16x16x32_bf16(Bt[n][k], At[m][k], acc[ai][bj][m][n], 0, 0, 0); __builtin_amdgcn_s_setprio(0); } while (0)
; #define PG8_WAIT_V(n) asm volatile("s_waitcnt vmcnt(" #n ")" ::: "memory")
; #define PG8_WAIT_L(n) asm volatile("s_waitcnt lgkmcnt(" #n ")" ::: "memory")
; #define PG8_BAR __builtin_amdgcn_s_barrier()
; #define PG8_SCHED __builtin_amdgcn_sched_barrier(0)
; __device__ __forceinline__ void gemm_phase(LAS unsigned char* lds, const Gemm g, const StaticOrder& S, const LAS Epi* Ep, const int tid) {
;     ...
;             PG8_WAIT_V(8); PG8_WAIT_L(0); PG8_BAR; PG8_MMA(1, 0, At, B0); PG8_MMA(1, 1, At, B1); PG8_BAR; PG8_SCHED;
;             PG8_LDB(B0, 1, 0); PG8_LDB(B1, 1, 1); PG8_SCHED; PG8_LDA(At, 1, 0); PG8_STAGE(PG8_SA(0, 1), a2 + hstepA, voffA);
;             PG8_WAIT_V(8); PG8_WAIT_L(0); PG8_BAR; PG8_MMA(0, 0, At, B0); PG8_MMA(0, 1, At, B1); PG8_BAR; PG8_SCHED;
	s_setprio 1
	s_waitcnt lgkmcnt(0)
	v_mfma_f32_16x16x32_bf16 v[64:67], v[132:135], v[164:167], 0
	v_mfma_f32_16x16x32_bf16 v[56:59], v[140:143], v[164:167], 0
	v_mfma_f32_16x16x32_bf16 v[48:51], v[132:135], v[172:175], 0
	v_mfma_f32_16x16x32_bf16 v[40:43], v[140:143], v[172:175], 0
	v_mfma_f32_16x16x32_bf16 v[32:35], v[132:135], v[180:183], 0
	v_mfma_f32_16x16x32_bf16 v[24:27], v[140:143], v[180:183], 0
	v_mfma_f32_16x16x32_bf16 v[16:19], v[132:135], v[188:191], 0
	v_mfma_f32_16x16x32_bf16 v[8:11], v[140:143], v[188:191], 0
	v_mfma_f32_16x16x32_bf16 v[64:67], v[136:139], v[168:171], v[64:67]
	v_mfma_f32_16x16x32_bf16 v[56:59], v[144:147], v[168:171], v[56:59]
	v_mfma_f32_16x16x32_bf16 v[48:51], v[136:139], v[176:179], v[48:51]
	v_mfma_f32_16x16x32_bf16 v[40:43], v[144:147], v[176:179], v[40:43]
	v_mfma_f32_16x16x32_bf16 v[32:35], v[136:139], v[184:187], v[32:35]
	v_mfma_f32_16x16x32_bf16 v[24:27], v[144:147], v[184:187], v[24:27]
	v_mfma_f32_16x16x32_bf16 v[16:19], v[136:139], v[192:195], v[16:19]
	v_mfma_f32_16x16x32_bf16 v[8:11], v[144:147], v[192:195], v[8:11]
	s_setprio 0
	s_setprio 1
	v_mfma_f32_16x16x32_bf16 v[60:63], v[148:151], v[164:167], 0
	v_mfma_f32_16x16x32_bf16 v[52:55], v[156:159], v[164:167], 0
	v_mfma_f32_16x16x32_bf16 v[44:47], v[148:151], v[172:175], 0
	v_mfma_f32_16x16x32_bf16 v[36:39], v[156:159], v[172:175], 0
	v_mfma_f32_16x16x32_bf16 v[28:31], v[148:151], v[180:183], 0
	v_mfma_f32_16x16x32_bf16 v[20:23], v[156:159], v[180:183], 0
	v_mfma_f32_16x16x32_bf16 v[12:15], v[148:151], v[188:191], 0
	v_mfma_f32_16x16x32_bf16 v[4:7], v[156:159], v[188:191], 0
	v_mfma_f32_16x16x32_bf16 v[60:63], v[152:155], v[168:171], v[60:63]
	v_mfma_f32_16x16x32_bf16 v[52:55], v[160:163], v[168:171], v[52:55]
	v_mfma_f32_16x16x32_bf16 v[44:47], v[152:155], v[176:179], v[44:47]
	v_mfma_f32_16x16x32_bf16 v[36:39], v[160:163], v[176:179], v[36:39]
	v_mfma_f32_16x16x32_bf16 v[28:31], v[152:155], v[184:187], v[28:31]
	v_mfma_f32_16x16x32_bf16 v[20:23], v[160:163], v[184:187], v[20:23]
	v_mfma_f32_16x16x32_bf16 v[12:15], v[152:155], v[192:195], v[12:15]
	v_mfma_f32_16x16x32_bf16 v[4:7], v[160:163], v[192:195], v[4:7]
	s_setprio 0
	s_barrier
	s_add_i32 s14, 0, 0x18000
	v_add_u32_e32 v2, s14, v230
	s_add_i32 s15, 0, 0x1c000
	ds_read_b128 v[132:135], v2
	ds_read_b128 v[136:139], v2 offset:1024
	ds_read_b128 v[140:143], v2 offset:2048
	ds_read_b128 v[144:147], v2 offset:3072
	v_add_u32_e32 v2, s15, v230
	ds_read_b128 v[148:151], v2
	ds_read_b128 v[152:155], v2 offset:1024
	ds_read_b128 v[156:159], v2 offset:2048
	ds_read_b128 v[160:163], v2 offset:3072
	s_add_u32 s10, s10, s58
	s_addc_u32 s11, s11, 0
	s_mov_b32 m0, s39
	v_lshl_add_u64 v[222:223], s[10:11], 0, v[0:1]
	ds_read_b128 v[164:167], v232 offset:32768
	ds_read_b128 v[168:171], v232 offset:33792
	ds_read_b128 v[172:175], v232 offset:34816
	ds_read_b128 v[176:179], v232 offset:35840
	ds_read_b128 v[180:183], v232 offset:36864
	ds_read_b128 v[184:187], v232 offset:37888
	ds_read_b128 v[188:191], v232 offset:38912
	ds_read_b128 v[192:195], v232 offset:39936
	global_load_lds_dwordx4 v[222:223], off
	v_lshl_add_u64 v[222:223], s[10:11], 0, v[198:199]
	s_mov_b32 m0, s88
	s_nop 0
	global_load_lds_dwordx4 v[222:223], off
	s_waitcnt vmcnt(8)
	s_waitcnt lgkmcnt(0)
	s_barrier
	s_setprio 1
	s_waitcnt lgkmcnt(0)
	v_mfma_f32_16x16x32_bf16 v[128:131], v[132:135], v[164:167], v[128:131]
	v_mfma_f32_16x16x32_bf16 v[120:123], v[140:143], v[164:167], v[120:123]
	v_mfma_f32_16x16x32_bf16 v[112:115], v[132:135], v[172:175], v[112:115]
	v_mfma_f32_16x16x32_bf16 v[104:107], v[140:143], v[172:175], v[104:107]
	v_mfma_f32_16x16x32_bf16 v[96:99], v[132:135], v[180:183], v[96:99]
	v_mfma_f32_16x16x32_bf16 v[88:91], v[140:143], v[180:183], v[88:91]
	v_mfma_f32_16x16x32_bf16 v[80:83], v[132:135], v[188:191], v[80:83]
	v_mfma_f32_16x16x32_bf16 v[72:75], v[140:143], v[188:191], v[72:75]
	v_mfma_f32_16x16x32_bf16 v[128:131], v[136:139], v[168:171], v[128:131]
	v_mfma_f32_16x16x32_bf16 v[120:123], v[144:147], v[168:171], v[120:123]
	v_mfma_f32_16x16x32_bf16 v[112:115], v[136:139], v[176:179], v[112:115]
	v_mfma_f32_16x16x32_bf16 v[104:107], v[144:147], v[176:179], v[104:107]
	v_mfma_f32_16x16x32_bf16 v[96:99], v[136:139], v[184:187], v[96:99]
	v_mfma_f32_16x16x32_bf16 v[88:91], v[144:147], v[184:187], v[88:91]
	v_mfma_f32_16x16x32_bf16 v[80:83], v[136:139], v[192:195], v[80:83]
	v_mfma_f32_16x16x32_bf16 v[72:75], v[144:147], v[192:195], v[72:75]
	s_setprio 0
	s_setprio 1
	v_mfma_f32_16x16x32_bf16 v[124:127], v[148:151], v[164:167], v[124:127]
	v_mfma_f32_16x16x32_bf16 v[116:119], v[156:159], v[164:167], v[116:119]
	v_mfma_f32_16x16x32_bf16 v[108:111], v[148:151], v[172:175], v[108:111]
	v_mfma_f32_16x16x32_bf16 v[100:103], v[156:159], v[172:175], v[100:103]
	v_mfma_f32_16x16x32_bf16 v[92:95], v[148:151], v[180:183], v[92:95]
	v_mfma_f32_16x16x32_bf16 v[84:87], v[156:159], v[180:183], v[84:87]
	v_mfma_f32_16x16x32_bf16 v[76:79], v[148:151], v[188:191], v[76:79]
	v_mfma_f32_16x16x32_bf16 v[68:71], v[156:159], v[188:191], v[68:71]
	v_mfma_f32_16x16x32_bf16 v[124:127], v[152:155], v[168:171], v[124:127]
	v_mfma_f32_16x16x32_bf16 v[116:119], v[160:163], v[168:171], v[116:119]
	v_mfma_f32_16x16x32_bf16 v[108:111], v[152:155], v[176:179], v[108:111]
	v_mfma_f32_16x16x32_bf16 v[100:103], v[160:163], v[176:179], v[100:103]
	v_mfma_f32_16x16x32_bf16 v[92:95], v[152:155], v[184:187], v[92:95]
	v_mfma_f32_16x16x32_bf16 v[84:87], v[160:163], v[184:187], v[84:87]
	v_mfma_f32_16x16x32_bf16 v[76:79], v[152:155], v[192:195], v[76:79]
	v_mfma_f32_16x16x32_bf16 v[68:71], v[160:163], v[192:195], v[68:71]
	s_setprio 0
	s_barrier
; #define PG8_STAGE(bufoff, gbase, voff) do { _Pragma("unroll") for (int _i = 0; _i < 2; ++_i) \
;         __builtin_amdgcn_global_load_lds((const unsigned*)((const char*)(gbase) + (voff)[_i]), (LAS unsigned*)(lds + (bufoff) + ldsw + _i * 8192), 16, 0, 0); } while (0)
; #define PG8_LDA(dst, b, h) do { _Pragma("unroll") for (int m = 0; m < 4; ++m) _Pragma("unroll") for (int k = 0; k < 2; ++k) dst[m][k] = *(const LAS bf16x8*)(lds + PG8_SA(b, h) + aoff + m * 2048 + k * 1024); } while (0)
; #define PG8_MMA(ai, bj, At, Bt) do { __builtin_amdgcn_s_setprio(1); _Pragma("unroll") for (int m = 0; m < 4; ++m) _Pragma("unroll") for (int n = 0; n < 2; ++n) _Pragma("unroll") for (int k = 0; k < 2; ++k) \
;         acc[ai][bj][m][n] = __builtin_amdgcn_mfma_f32_16x16x32_bf16(Bt[n][k], At[m][k], acc[ai][bj][m][n], 0, 0, 0); __builtin_amdgcn_s_setprio(0); } while (0)
; #define PG8_WAIT_V(n) asm volatile("s_waitcnt vmcnt(" #n ")" ::: "memory")
; #define PG8_WAIT_L(n) asm volatile("s_waitcnt lgkmcnt(" #n ")" ::: "memory")
; #define PG8_BAR __builtin_amdgcn_s_barrier()
; #define PG8_SCHED __builtin_amdgcn_sched_barrier(0)
; __device__ __forceinline__ void gemm_phase(LAS unsigned char* lds, const Gemm g, const StaticOrder& S, const LAS Epi* Ep, const int tid) {
;     ...
;             PG8_WAIT_V(8); PG8_WAIT_L(0); PG8_BAR; PG8_MMA(0, 0, At, B0); PG8_MMA(0, 1, At, B1); PG8_BAR; PG8_SCHED;
;             PG8_LDA(At, 1, 1); PG8_STAGE(PG8_SB(1, 0), b3, voffB); PG8_STAGE(PG8_SB(1, 1), b3 + hstepB, voffB); PG8_STAGE(PG8_SA(1, 0), a3, voffA);
;             PG8_WAIT_V(8); PG8_WAIT_L(0); PG8_BAR; PG8_MMA(1, 0, At, B0); PG8_MMA(1, 1, At, B1); PG8_BAR; PG8_SCHED;
;         }
	s_add_i32 s10, s14, s86
	v_lshl_add_u64 v[210:211], v[210:211], 0, s[90:91]
	s_mov_b32 m0, s10
	ds_read_b128 v[164:167], v232 offset:49152
	ds_read_b128 v[168:171], v232 offset:50176
	ds_read_b128 v[172:175], v232 offset:51200
	ds_read_b128 v[176:179], v232 offset:52224
	ds_read_b128 v[180:183], v232 offset:53248
	ds_read_b128 v[184:187], v232 offset:54272
	ds_read_b128 v[188:191], v232 offset:55296
	ds_read_b128 v[192:195], v232 offset:56320
	global_load_lds_dwordx4 v[210:211], off
	v_lshl_add_u64 v[210:211], v[212:213], 0, s[90:91]
	s_add_i32 m0, s10, 0x2000
	s_add_i32 s10, s15, s86
	global_load_lds_dwordx4 v[210:211], off
	v_lshl_add_u64 v[210:211], v[214:215], 0, s[90:91]
	s_mov_b32 m0, s10
	s_nop 0
	global_load_lds_dwordx4 v[210:211], off
	v_lshl_add_u64 v[210:211], v[216:217], 0, s[90:91]
	s_add_i32 m0, s10, 0x2000
	s_nop 0
	global_load_lds_dwordx4 v[210:211], off
	v_lshl_add_u64 v[210:211], v[218:219], 0, s[90:91]
	s_mov_b32 m0, s89
	s_nop 0
	global_load_lds_dwordx4 v[210:211], off
	v_lshl_add_u64 v[210:211], v[220:221], 0, s[90:91]
	s_mov_b32 m0, s36
	s_nop 0
	global_load_lds_dwordx4 v[210:211], off
	s_waitcnt vmcnt(8)
	s_waitcnt lgkmcnt(0)
	s_barrier
	s_setprio 1
	s_waitcnt lgkmcnt(0)
	v_mfma_f32_16x16x32_bf16 v[64:67], v[132:135], v[164:167], v[64:67]
	v_mfma_f32_16x16x32_bf16 v[56:59], v[140:143], v[164:167], v[56:59]
	v_mfma_f32_16x16x32_bf16 v[48:51], v[132:135], v[172:175], v[48:51]
	v_mfma_f32_16x16x32_bf16 v[40:43], v[140:143], v[172:175], v[40:43]
	v_mfma_f32_16x16x32_bf16 v[32:35], v[132:135], v[180:183], v[32:35]
	v_mfma_f32_16x16x32_bf16 v[24:27], v[140:143], v[180:183], v[24:27]
	v_mfma_f32_16x16x32_bf16 v[16:19], v[132:135], v[188:191], v[16:19]
	v_mfma_f32_16x16x32_bf16 v[8:11], v[140:143], v[188:191], v[8:11]
	v_mfma_f32_16x16x32_bf16 v[64:67], v[136:139], v[168:171], v[64:67]
	v_mfma_f32_16x16x32_bf16 v[56:59], v[144:147], v[168:171], v[56:59]
	v_mfma_f32_16x16x32_bf16 v[48:51], v[136:139], v[176:179], v[48:51]
	v_mfma_f32_16x16x32_bf16 v[40:43], v[144:147], v[176:179], v[40:43]
	v_mfma_f32_16x16x32_bf16 v[32:35], v[136:139], v[184:187], v[32:35]
	v_mfma_f32_16x16x32_bf16 v[24:27], v[144:147], v[184:187], v[24:27]
	v_mfma_f32_16x16x32_bf16 v[16:19], v[136:139], v[192:195], v[16:19]
	v_mfma_f32_16x16x32_bf16 v[8:11], v[144:147], v[192:195], v[8:11]
	s_setprio 0
	s_setprio 1
	v_mfma_f32_16x16x32_bf16 v[60:63], v[148:151], v[164:167], v[60:63]
	v_mfma_f32_16x16x32_bf16 v[52:55], v[156:159], v[164:167], v[52:55]
	v_mfma_f32_16x16x32_bf16 v[44:47], v[148:151], v[172:175], v[44:47]
	v_mfma_f32_16x16x32_bf16 v[36:39], v[156:159], v[172:175], v[36:39]
	v_mfma_f32_16x16x32_bf16 v[28:31], v[148:151], v[180:183], v[28:31]
	v_mfma_f32_16x16x32_bf16 v[20:23], v[156:159], v[180:183], v[20:23]
	v_mfma_f32_16x16x32_bf16 v[12:15], v[148:151], v[188:191], v[12:15]
	v_mfma_f32_16x16x32_bf16 v[4:7], v[156:159], v[188:191], v[4:7]
	v_mfma_f32_16x16x32_bf16 v[60:63], v[152:155], v[168:171], v[60:63]
	v_mfma_f32_16x16x32_bf16 v[52:55], v[160:163], v[168:171], v[52:55]
	v_mfma_f32_16x16x32_bf16 v[44:47], v[152:155], v[176:179], v[44:47]
	v_mfma_f32_16x16x32_bf16 v[36:39], v[160:163], v[176:179], v[36:39]
	v_mfma_f32_16x16x32_bf16 v[28:31], v[152:155], v[184:187], v[28:31]
	v_mfma_f32_16x16x32_bf16 v[20:23], v[160:163], v[184:187], v[20:23]
	v_mfma_f32_16x16x32_bf16 v[12:15], v[152:155], v[192:195], v[12:15]
	v_mfma_f32_16x16x32_bf16 v[4:7], v[160:163], v[192:195], v[4:7]
	s_setprio 0
	s_barrier
	s_add_u32 s0, s0, 0x100
	s_addc_u32 s1, s1, 0
	s_add_u32 s3, s3, 0x100
	s_addc_u32 s12, s12, 0
	s_cmp_ge_u32 s13, s70
	s_mov_b32 s10, s13
	s_cbranch_scc0 .LBB0_1846
	s_branch .Lpeel3_exit
	.p2alignl 6, 3212836864
